# v19 + P0 table loops placed so GEMV blocks get at most one heavy table loop and the non-GEMV blocks absorb the rest
# baseline (speedup 1.0000x reference)
.LBB0_38:
	s_or_b64 exec, exec, s[8:9]
	s_mov_b32 s0, 0x10000
	v_or_b32_e32 v135, 4, v160
	v_or_b32_e32 v139, 8, v160
	v_or_b32_e32 v141, 12, v160
	v_or_b32_e32 v143, 16, v160
	v_or_b32_e32 v145, 20, v160
	v_or_b32_e32 v147, 24, v160
	v_or_b32_e32 v149, 28, v160
	v_or_b32_e32 v151, 32, v160
	v_or_b32_e32 v152, 36, v160
	v_or_b32_e32 v153, 40, v160
	v_or_b32_e32 v154, 44, v160
	v_or_b32_e32 v155, 48, v160
	v_or_b32_e32 v156, 52, v160
	v_or_b32_e32 v157, 56, v160
	v_or_b32_e32 v158, 60, v160
	s_sub_u32 s32, s2, 128
	s_and_b32 s32, s32, 0xff
	v_lshl_add_u32 v6, s32, 9, v190
	v_cmp_gt_i32_e32 vcc, s0, v6
	s_and_saveexec_b64 s[10:11], vcc
	s_cbranch_execz .LBB0_47
	v_and_b32_e32 v1, 1, v190
	v_lshl_add_u64 v[2:3], v[6:7], 4, s[62:63]
	s_mov_b64 s[0:1], 0x200000
	s_ashr_i32 s19, s18, 31
	v_cmp_eq_u32_e64 s[4:5], 0, v1
	v_lshl_add_u64 v[8:9], v[2:3], 0, s[0:1]
	s_lshl_b64 s[12:13], s[18:19], 4
	s_mov_b64 s[14:15], 0
	s_mov_b32 s19, 0x3fb8aa3b
	s_mov_b32 s22, 0xc2ce8ed0
	s_mov_b32 s23, 0x42b17218
	v_mov_b32_e32 v11, 0
	s_mov_b32 s24, 0xbfc90fda
	v_mov_b32_e32 v1, 0x3c0881c4
	v_mov_b32_e32 v12, 0xbab64f3b
	s_brev_b32 s25, 1
	s_movk_i32 s27, 0x1f8
	s_mov_b32 s28, 0xffff
	v_mov_b32_e32 v13, 0x7f800000
	v_not_b32_e32 v14, 63
	v_not_b32_e32 v15, 31
	v_mov_b32_e32 v16, 0x7fc00000
	v_mov_b32_e32 v17, v6
	s_branch .LBB0_42

.LBB0_47:
	s_or_b64 exec, exec, s[10:11]
	s_mov_b32 s0, 0x8000
	s_sub_u32 s32, s2, 192
	s_and_b32 s32, s32, 0xff
	v_lshl_add_u32 v6, s32, 9, v190
	v_cmp_gt_i32_e32 vcc, s0, v6
	s_and_saveexec_b64 s[0:1], vcc
	v_readlane_b32 s64, v254, 22
	v_readlane_b32 s66, v254, 24
	v_readlane_b32 s67, v254, 25
	v_readlane_b32 s68, v254, 26
	v_readlane_b32 s69, v254, 27
	v_readlane_b32 s65, v254, 23
	v_readlane_b32 s70, v254, 28
	v_readlane_b32 s71, v254, 29
	v_readlane_b32 s72, v254, 30
	v_readlane_b32 s73, v254, 31
	v_readlane_b32 s74, v254, 32
	v_readlane_b32 s75, v254, 33
	v_readlane_b32 s76, v254, 34
	v_readlane_b32 s77, v254, 35
	v_readlane_b32 s78, v254, 36
	v_readlane_b32 s79, v254, 37
	s_cbranch_execz .LBB0_50
	v_lshl_add_u64 v[2:3], v[6:7], 4, s[62:63]
	s_mov_b64 s[4:5], 0x300000
	s_ashr_i32 s19, s18, 31
	v_lshlrev_b32_e32 v1, 6, v190
	v_lshl_add_u64 v[2:3], v[2:3], 0, s[4:5]
	s_lshl_b64 s[4:5], s[18:19], 4
	v_lshl_add_u32 v1, s32, 15, v1
	s_lshl_b32 s8, s33, 15
	s_mov_b64 s[6:7], 0
	s_movk_i32 s9, 0xffc0
	v_mov_b32_e32 v5, 0
	s_movk_i32 s10, 0x7fff
	v_mov_b32_e32 v8, v6

.LBB0_50:
	s_or_b64 exec, exec, s[0:1]
	s_mov_b32 s0, 0xc000
	s_sub_u32 s32, s2, 160
	s_and_b32 s32, s32, 0xff
	v_lshl_add_u32 v6, s32, 9, v190
	v_cmp_gt_i32_e32 vcc, s0, v6
	s_and_saveexec_b64 s[4:5], vcc
	s_cbranch_execz .LBB0_58
	v_cvt_f32_u32_e32 v2, s18
	v_add_u32_e32 v1, s18, v6
	v_mov_b32_e32 v3, s18
	v_cmp_gt_i32_e32 vcc, s0, v1
	v_rcp_iflag_f32_e32 v2, v2
	s_sub_i32 s6, 0, s18
	v_max_i32_e32 v4, 0xc000, v1
	v_addc_co_u32_e64 v3, s[0:1], v6, v3, vcc
	v_mul_f32_e32 v2, 0x4f7ffffe, v2
	v_cvt_u32_f32_e32 v2, v2
	v_sub_u32_e32 v3, v4, v3
	v_mul_lo_u32 v4, s6, v2
	v_mul_hi_u32 v4, v2, v4
	v_add_u32_e32 v2, v2, v4
	v_mul_hi_u32 v2, v3, v2
	v_mul_lo_u32 v4, v2, s18
	v_sub_u32_e32 v3, v3, v4
	v_add_u32_e32 v5, 1, v2
	v_cmp_le_u32_e64 s[0:1], s18, v3
	v_subrev_u32_e32 v4, s18, v3
	s_mov_b64 s[6:7], -1
	v_cndmask_b32_e64 v2, v2, v5, s[0:1]
	v_cndmask_b32_e64 v3, v3, v4, s[0:1]
	v_add_u32_e32 v4, 1, v2
	v_cmp_le_u32_e64 s[0:1], s18, v3
	s_nop 1
	v_cndmask_b32_e64 v2, v2, v4, s[0:1]
	v_addc_co_u32_e32 v4, vcc, 1, v2, vcc
	v_cmp_lt_u32_e32 vcc, 1, v4
	v_mov_b32_e32 v2, v6
	s_and_saveexec_b64 s[0:1], vcc
	s_cbranch_execz .LBB0_55
	s_add_u32 s6, s62, 0x500000
	s_addc_u32 s7, s63, 0
	v_and_b32_e32 v5, -2, v4
	s_lshl_b32 s10, s33, 10
	v_mov_b32_e32 v2, v6
	s_mov_b32 s11, s10
	s_mov_b64 s[8:9], 0
	v_mov_b32_e32 v3, 0
	v_mov_b32_e32 v8, v5

.LBB0_58:
	s_or_b64 exec, exec, s[4:5]
	s_movk_i32 s0, 0x4000
	s_sub_u32 s32, s2, 192
	s_and_b32 s32, s32, 0xff
	v_lshl_add_u32 v6, s32, 9, v190
	v_cmp_gt_i32_e32 vcc, s0, v6
	s_and_saveexec_b64 s[0:1], vcc
	s_cbranch_execz .LBB0_61
	v_lshlrev_b64 v[2:3], 5, v[6:7]
	v_lshl_add_u64 v[2:3], s[82:83], 0, v[2:3]
	s_ashr_i32 s19, s18, 31
	v_lshl_add_u64 v[4:5], v[6:7], 4, s[62:63]
	s_mov_b64 s[6:7], 0x700000
	v_lshl_add_u64 v[2:3], v[2:3], 0, 16
	s_lshl_b64 s[4:5], s[18:19], 5
	v_lshl_add_u64 v[4:5], v[4:5], 0, s[6:7]
	s_lshl_b64 s[6:7], s[18:19], 4
	s_mov_b64 s[8:9], 0
	s_movk_i32 s10, 0x3fff
	v_mov_b32_e32 v1, v6

.LBB0_61:
	s_or_b64 exec, exec, s[0:1]
	s_mov_b32 s0, 0x14000
	s_sub_u32 s32, s2, 192
	s_and_b32 s32, s32, 0xff
	v_lshl_add_u32 v6, s32, 9, v190
	v_cmp_gt_i32_e32 vcc, s0, v6
	s_and_saveexec_b64 s[8:9], vcc
	s_cbranch_execz .LBB0_76
	v_and_b32_e32 v1, 0x1ff, v190
	v_cvt_f32_u32_e32 v1, v1
	v_mov_b32_e32 v2, 0x461c4000
	s_mov_b32 s0, 0x3f2aaaab
	s_mov_b32 s1, 0x42b17218
	v_mul_f32_e32 v1, 0x3b000000, v1
	v_cmp_eq_f32_e32 vcc, 0, v1
	s_mov_b32 s5, 0x3fb8aa3b
	s_mov_b32 s4, 0x7f800000
	v_cndmask_b32_e64 v14, v2, 1.0, vcc
	v_frexp_mant_f32_e32 v2, v14
	v_cmp_gt_f32_e32 vcc, s0, v2
	s_mov_b32 s0, 0x3f317218
	s_ashr_i32 s19, s18, 31
	v_cndmask_b32_e64 v3, 1.0, 2.0, vcc
	v_mul_f32_e32 v2, v2, v3
	v_add_f32_e32 v5, 1.0, v2
	v_rcp_f32_e32 v12, v5
	v_add_f32_e32 v3, -1.0, v5
	v_sub_f32_e32 v9, v2, v3
	v_add_f32_e32 v3, -1.0, v2
	v_mul_f32_e32 v13, v3, v12
	v_mul_f32_e32 v4, v5, v13
	v_fma_f32 v8, v13, v5, -v4
	v_fmac_f32_e32 v8, v13, v9
	v_add_f32_e32 v2, v4, v8
	v_sub_f32_e32 v5, v3, v2
	v_pk_add_f32 v[10:11], v[2:3], v[4:5] neg_lo:[0,1] neg_hi:[0,1]
	v_mov_b32_e32 v9, v2
	v_pk_add_f32 v[2:3], v[10:11], v[8:9] neg_lo:[0,1] neg_hi:[0,1]
	v_mov_b32_e32 v8, 0x3e91f4c4
	v_add_f32_e32 v2, v2, v3
	v_add_f32_e32 v2, v5, v2
	v_mul_f32_e32 v3, v12, v2
	v_add_f32_e32 v2, v13, v3
	v_sub_f32_e32 v4, v2, v13
	v_sub_f32_e32 v15, v3, v4
	v_mul_f32_e32 v3, v2, v2
	v_fma_f32 v5, v2, v2, -v3
	v_add_f32_e32 v4, v15, v15
	v_fmac_f32_e32 v5, v2, v4
	v_add_f32_e32 v4, v3, v5
	v_fmac_f32_e32 v8, 0x3e76c4e1, v4
	v_fmaak_f32 v8, v4, v8, 0x3ecccdef
	v_sub_f32_e32 v3, v4, v3
	v_sub_f32_e32 v16, v5, v3
	v_mul_f32_e32 v3, v4, v8
	v_fma_f32 v5, v4, v8, -v3
	v_fmac_f32_e32 v5, v16, v8
	v_add_f32_e32 v8, v3, v5
	v_add_f32_e32 v9, 0x3f2aaaaa, v8
	v_sub_f32_e32 v3, v8, v3
	v_sub_f32_e32 v3, v5, v3
	v_add_f32_e32 v5, 0xbf2aaaaa, v9
	v_add_f32_e32 v3, 0x31739010, v3
	v_sub_f32_e32 v5, v8, v5
	v_pk_mul_f32 v[10:11], v[2:3], v[4:5]
	v_pk_add_f32 v[12:13], v[2:3], v[4:5]
	v_fma_f32 v8, v4, v2, -v10
	v_fmac_f32_e32 v8, v4, v15
	v_mov_b32_e32 v11, v13
	v_fmac_f32_e32 v8, v16, v2
	v_pk_add_f32 v[4:5], v[10:11], v[8:9]
	v_ldexp_f32 v16, v15, 1
	v_sub_f32_e32 v3, v4, v10
	v_sub_f32_e32 v3, v8, v3
	v_sub_f32_e32 v8, v9, v5
	v_add_f32_e32 v11, v13, v8
	v_pk_mul_f32 v[8:9], v[4:5], v[4:5] op_sel:[0,1] op_sel_hi:[1,0]
	v_cvt_f64_f32_e32 v[12:13], v14
	v_frexp_exp_i32_f64_e32 v9, v[12:13]
	v_subbrev_co_u32_e32 v9, vcc, 0, v9, vcc
	v_cvt_f32_i32_e32 v9, v9
	v_fma_f32 v10, v4, v5, -v8
	v_fmac_f32_e32 v10, v4, v11
	v_fmac_f32_e32 v10, v3, v5
	v_mul_f32_e32 v4, 0x3f317218, v9
	v_fma_f32 v3, v9, s0, -v4
	v_fmamk_f32 v12, v9, 0xb102e308, v3
	v_ldexp_f32 v13, v2, 1
	v_add_f32_e32 v5, v8, v10
	v_pk_add_f32 v[2:3], v[4:5], v[12:13]
	v_mov_b32_e32 v14, v5
	v_mov_b32_e32 v15, v3
	v_mov_b32_e32 v9, v13
	v_pk_add_f32 v[8:9], v[14:15], v[8:9] neg_lo:[0,1] neg_hi:[0,1]
	v_mov_b32_e32 v11, v5
	v_pk_add_f32 v[8:9], v[10:11], v[8:9] neg_lo:[0,1] neg_hi:[0,1]
	v_mov_b32_e32 v13, v2
	v_add_f32_e32 v5, v16, v8
	v_add_f32_e32 v5, v5, v9
	v_pk_add_f32 v[8:9], v[2:3], v[4:5] neg_lo:[0,1] neg_hi:[0,1]
	v_pk_add_f32 v[10:11], v[2:3], v[4:5]
	v_mov_b32_e32 v4, v5
	v_mov_b32_e32 v9, v11
	v_pk_add_f32 v[14:15], v[12:13], v[8:9] neg_lo:[0,1] neg_hi:[0,1]
	v_pk_add_f32 v[8:9], v[12:13], v[8:9]
	v_mov_b32_e32 v5, v2
	v_pk_add_f32 v[12:13], v[8:9], v[2:3] op_sel:[1,0] op_sel_hi:[0,1] neg_lo:[0,1] neg_hi:[0,1]
	v_pk_add_f32 v[16:17], v[10:11], v[12:13] op_sel_hi:[1,0] neg_lo:[0,1] neg_hi:[0,1]
	v_mov_b32_e32 v10, v11
	v_mov_b32_e32 v11, v9
	v_pk_mov_b32 v[12:13], v[2:3], v[12:13] op_sel:[1,0]
	v_mov_b32_e32 v16, v14
	v_pk_add_f32 v[10:11], v[10:11], v[12:13] neg_lo:[0,1] neg_hi:[0,1]
	v_mov_b32_e32 v15, v9
	v_pk_add_f32 v[2:3], v[4:5], v[10:11] neg_lo:[0,1] neg_hi:[0,1]
	s_movk_i32 s0, 0x204
	v_pk_add_f32 v[4:5], v[16:17], v[2:3]
	s_lshl_b64 s[10:11], s[18:19], 2
	v_pk_add_f32 v[10:11], v[4:5], v[4:5] op_sel:[0,1] op_sel_hi:[1,0]
	s_mov_b64 s[12:13], 0
	v_pk_add_f32 v[8:9], v[8:9], v[10:11] op_sel:[1,0] op_sel_hi:[0,1]
	v_mov_b32_e32 v5, v8
	v_pk_add_f32 v[12:13], v[4:5], v[14:15] neg_lo:[0,1] neg_hi:[0,1]
	v_mov_b32_e32 v3, v10
	v_sub_f32_e32 v4, v4, v12
	v_pk_add_f32 v[2:3], v[2:3], v[12:13] neg_lo:[0,1] neg_hi:[0,1]
	v_sub_f32_e32 v4, v14, v4
	v_add_f32_e32 v2, v2, v4
	v_add_f32_e32 v2, v2, v3
	v_add_f32_e32 v3, v8, v2
	v_sub_f32_e32 v4, v3, v8
	v_sub_f32_e32 v2, v2, v4
	v_mul_f32_e32 v4, v1, v3
	v_fma_f32 v3, v1, v3, -v4
	v_fmac_f32_e32 v3, v1, v2
	v_add_f32_e32 v2, v4, v3
	v_cmp_class_f32_e64 vcc, v4, s0
	v_sub_f32_e32 v5, v2, v4
	v_sub_f32_e32 v3, v3, v5
	v_cndmask_b32_e32 v2, v2, v4, vcc
	v_mov_b32_e32 v4, 0x37000000
	v_cmp_eq_f32_e32 vcc, s1, v2
	s_brev_b32 s19, 18
	s_mov_b32 s22, 0xfe5163ab
	v_cndmask_b32_e32 v4, 0, v4, vcc
	v_sub_f32_e32 v5, v2, v4
	v_mul_f32_e32 v8, 0x3fb8aa3b, v5
	v_fma_f32 v9, v5, s5, -v8
	v_rndne_f32_e32 v10, v8
	v_fmamk_f32 v9, v5, 0x32a5705f, v9
	v_sub_f32_e32 v8, v8, v10
	v_add_f32_e32 v8, v8, v9
	v_exp_f32_e32 v8, v8
	v_cvt_i32_f32_e32 v9, v10
	v_cmp_neq_f32_e64 vcc, |v2|, s4
	s_mov_b32 s5, 0xc2ce8ed0
	s_mov_b32 s23, 0x3c439041
	v_cndmask_b32_e32 v2, 0, v3, vcc
	v_ldexp_f32 v3, v8, v9
	v_cmp_ngt_f32_e32 vcc, s5, v5
	v_add_f32_e32 v2, v4, v2
	v_mov_b32_e32 v4, 0x7f800000
	v_cndmask_b32_e32 v3, 0, v3, vcc
	v_cmp_nlt_f32_e32 vcc, s1, v5
	s_mov_b32 s24, 0xdb629599
	s_mov_b32 s25, 0xf534ddc0
	v_cndmask_b32_e32 v3, v4, v3, vcc
	v_fma_f32 v2, v3, v2, v3
	v_cmp_class_f32_e64 vcc, v3, s0
	s_mov_b32 s27, 0xfc2757d1
	s_mov_b32 s28, 0x4e441529
	v_cndmask_b32_e32 v2, v2, v3, vcc
	v_and_b32_e32 v3, 0x7fffffff, v2
	v_div_scale_f32 v4, s[0:1], v3, v3, 1.0
	v_rcp_f32_e32 v5, v4
	v_div_scale_f32 v3, vcc, 1.0, v3, 1.0
	s_mov_b64 s[0:1], 0x80000
	v_fma_f32 v8, -v4, v5, 1.0
	v_fmac_f32_e32 v5, v8, v5
	v_mul_f32_e32 v8, v3, v5
	v_fma_f32 v9, -v4, v8, v3
	v_fmac_f32_e32 v8, v9, v5
	v_fma_f32 v3, -v4, v8, v3
	v_div_fmas_f32 v3, v3, v5, v8
	v_div_fixup_f32 v2, v3, |v2|, 1.0
	v_cmp_neq_f32_e32 vcc, s4, v1
	v_mov_b32_e32 v5, 0
	s_mov_b32 s29, 0xa2f9836e
	v_cndmask_b32_e32 v1, 0, v2, vcc
	v_lshl_add_u64 v[2:3], v[6:7], 2, s[62:63]
	v_lshl_add_u64 v[2:3], v[2:3], 0, s[0:1]
	s_mov_b32 s30, 0x3fc90fda
	s_mov_b32 s31, 0x3f22f983
	s_mov_b32 s34, 0xbfc90fda
	v_mov_b32_e32 v7, 0x3c0881c4
	v_mov_b32_e32 v8, 0xbab64f3b
	s_brev_b32 s35, 1
	s_movk_i32 s36, 0x1f8
	s_mov_b32 s37, 0x13fff
	v_not_b32_e32 v9, 63
	v_not_b32_e32 v10, 31
	v_mov_b32_e32 v11, 0x7fc00000
	s_branch .LBB0_65
